# combo + next-layer weight-conversion quotas rebalanced across GEMM tails (4500/9000/11012 instead of 6400/12500/5612)
# baseline (speedup 1.0000x reference)
.LBB0_315:
	s_cmp_eq_u32 s50, 3
	s_cbranch_scc1 .LBB0_328
	s_abs_i32 s8, s34
	v_cvt_f32_u32_e32 v0, s8
	s_sub_i32 s9, 0, s8
	v_rcp_iflag_f32_e32 v0, v0
	s_nop 0
	v_mul_f32_e32 v0, 0x4f7ffffe, v0
	v_cvt_u32_f32_e32 v0, v0
	s_nop 0
	v_readfirstlane_b32 s12, v0
	s_mul_i32 s9, s9, s12
	s_mul_hi_u32 s9, s12, s9
	s_add_i32 s12, s12, s9
	s_mul_hi_u32 s9, s12, 0x5ab
	s_mul_i32 s9, s9, s8
	s_sub_i32 s9, 0x5ab, s9
	s_sub_i32 s12, s9, s8
	s_cmp_ge_u32 s9, s8
	s_cselect_b32 s9, s12, s9
	s_sub_i32 s12, s9, s8
	s_cmp_ge_u32 s9, s8
	s_cselect_b32 s8, s12, s9
	s_add_i32 s8, s8, 1
	s_cmp_lt_i32 s8, s34
	s_cselect_b32 s20, s8, 0
	s_cmp_lt_i32 s36, s20
	s_cbranch_scc1 .LBB0_328
	s_add_i32 s8, s50, 1
	s_bitcmp1_b32 s8, 0
	s_cselect_b32 s21, 0x6000000, 0
	s_sub_i32 s9, s36, s20
	s_lshl_b32 s22, s9, 3
	s_add_i32 s22, s22, s35
	v_and_b32_e32 v1, 63, v164
	s_cmpk_gt_i32 s22, 0x1193
	s_waitcnt vmcnt(0)
	s_barrier
	s_cbranch_scc1 .LBB0_324
	s_ashr_i32 s41, s40, 31
	s_lshl_b64 s[12:13], s[40:41], 3
	v_readlane_b32 s16, v253, 5
	v_readlane_b32 s17, v253, 6
	s_add_u32 s12, s16, s12
	s_addc_u32 s13, s17, s13
	s_load_dwordx2 s[16:17], s[12:13], 0x38
	s_mul_i32 s9, s8, 0x2b80000
	s_load_dwordx2 s[12:13], s[12:13], 0xa0
	s_lshl_b32 s88, s8, 11
	s_mul_hi_u32 s18, s88, 0x5700
	s_waitcnt lgkmcnt(0)
	s_add_u32 s8, s16, s9
	s_addc_u32 s9, s17, s18
	s_lshl_b64 s[16:17], s[88:89], 13
	s_add_u32 s12, s12, s16
	s_addc_u32 s13, s13, s17
	s_lshl_b32 s16, s35, 14
	s_add_i32 s18, s16, 0
	v_lshlrev_b32_e32 v2, 3, v1
	s_add_u32 s16, s44, s21
	v_and_b32_e32 v2, 56, v2
	s_addc_u32 s17, s45, 0
	v_mul_u32_u24_e32 v36, 0x84, v2
	v_lshlrev_b32_e32 v2, 1, v2
	v_lshl_add_u64 v[30:31], s[16:17], 0, v[2:3]
	s_mov_b64 s[16:17], 0xbc00000
	v_lshrrev_b32_e32 v34, 5, v1
	v_and_b32_e32 v0, 31, v164
	v_lshrrev_b32_e32 v35, 3, v1
	v_lshl_add_u64 v[28:29], v[30:31], 0, s[16:17]
	s_mov_b64 s[16:17], 0xa600000
	v_lshl_add_u32 v32, v0, 2, s18
	v_mul_u32_u24_e32 v33, 0x84, v34
	v_lshlrev_b32_e32 v2, 2, v35
	v_lshl_add_u64 v[30:31], v[30:31], 0, s[16:17]
	s_sub_i32 s16, s34, s20
	v_add3_u32 v36, s18, v36, v2
	v_or_b32_e32 v37, 8, v35
	v_or_b32_e32 v38, 16, v35
	v_or_b32_e32 v39, 24, v35
	s_lshl_b32 s23, s16, 3
	s_lshl_b32 s24, s22, 5
	s_lshl_b32 s25, s16, 8
	v_add_u32_e32 v40, v32, v33
	s_mov_b32 s26, s22
	s_branch .LBB0_320
.LBB0_319:
	s_add_i32 s26, s26, s23
	s_add_i32 s24, s24, s25
	s_cmpk_gt_i32 s26, 0x1193
	s_cbranch_scc1 .LBB0_324

.LBB0_1587:
	s_andn2_b64 vcc, exec, s[44:45]
	s_cbranch_vccnz .LBB0_1608
	s_abs_i32 s8, s20
	v_cvt_f32_u32_e32 v0, s8
	s_sub_i32 s16, 0, s8
	s_add_i32 s9, s88, -1
	s_abs_i32 s13, s9
	v_rcp_iflag_f32_e32 v0, v0
	s_ashr_i32 s12, s9, 31
	v_mul_f32_e32 v0, 0x4f7ffffe, v0
	v_cvt_u32_f32_e32 v0, v0
	s_nop 0
	v_readfirstlane_b32 s17, v0
	s_mul_i32 s16, s16, s17
	s_mul_hi_u32 s16, s17, s16
	s_add_i32 s17, s17, s16
	s_mul_hi_u32 s16, s13, s17
	s_mul_i32 s16, s16, s8
	s_sub_i32 s13, s13, s16
	s_sub_i32 s16, s13, s8
	s_cmp_ge_u32 s13, s8
	s_cselect_b32 s13, s16, s13
	s_sub_i32 s16, s13, s8
	s_cmp_ge_u32 s13, s8
	s_cselect_b32 s8, s16, s13
	s_xor_b32 s8, s8, s12
	s_sub_i32 s8, s8, s12
	s_sub_i32 s8, s8, s9
	s_add_i32 s8, s8, s88
	s_cmp_lt_i32 s8, s20
	s_cselect_b32 s8, s8, 0
	s_cmp_lt_i32 s22, s8
	s_cbranch_scc1 .LBB0_1608
	s_sub_i32 s9, s22, s8
	s_lshl_b32 s9, s9, 3
	s_add_i32 s9, s21, s9
	s_add_i32 s16, s9, 0x1194
	s_cmpk_gt_i32 s16, 0x34bb
	s_waitcnt vmcnt(0)
	s_barrier
	s_cbranch_scc1 .LBB0_1608
	s_ashr_i32 s43, s42, 31
	s_add_i32 s88, s50, 1
	s_lshl_b64 s[12:13], s[42:43], 3
	v_readlane_b32 s18, v253, 5
	v_readlane_b32 s19, v253, 6
	s_add_u32 s12, s18, s12
	s_addc_u32 s13, s19, s13
	s_load_dwordx2 s[18:19], s[12:13], 0x38
	s_load_dwordx2 s[22:23], s[12:13], 0xa0
	s_mul_i32 s17, s88, 0x2b80000
	s_load_dwordx4 s[24:27], s[12:13], 0xb0
	s_mul_hi_u32 s9, s88, 0x2b80000
	s_waitcnt lgkmcnt(0)
	s_add_u32 s38, s18, s17
	s_addc_u32 s39, s19, s9
	s_lshl_b64 s[18:19], s[88:89], 24
	s_add_u32 s42, s22, s18
	s_addc_u32 s43, s23, s19
	s_mul_i32 s17, s88, 0x2c00000
	s_load_dwordx2 s[12:13], s[12:13], 0xc0
	s_mul_hi_u32 s9, s88, 0x2c00000
	s_add_u32 s44, s24, s17
	s_addc_u32 s45, s25, s9
	s_add_u32 s46, s26, s17
	s_addc_u32 s47, s27, s9
	s_waitcnt lgkmcnt(0)
	s_add_u32 s12, s12, s17
	s_addc_u32 s13, s13, s9
	s_bitcmp1_b32 s88, 0
	v_bfe_u32 v1, v166, 5, 1
	s_cselect_b32 s9, 0x6000000, 0
	s_lshl_b32 s17, s21, 14
	v_lshlrev_b32_e32 v2, 13, v1
	v_and_b32_e32 v0, 31, v166
	s_add_i32 s17, s17, 0
	v_lshl_add_u64 v[28:29], s[12:13], 0, v[2:3]
	v_lshlrev_b32_e32 v2, 2, v0
	v_mul_u32_u24_e32 v30, 0x84, v1
	v_lshl_add_u64 v[28:29], v[28:29], 0, v[2:3]
	v_add3_u32 v40, s17, v2, v30
	v_lshlrev_b32_e32 v2, 3, v166
	s_add_u32 s18, s40, s9
	v_and_b32_e32 v2, 56, v2
	s_addc_u32 s19, s41, 0
	v_mul_u32_u24_e32 v32, 0x84, v2
	v_lshlrev_b32_e32 v2, 1, v2
	v_bfe_u32 v41, v166, 3, 3
	v_lshl_add_u64 v[36:37], s[18:19], 0, v[2:3]
	s_mov_b64 s[12:13], 0xf000000
	v_lshl_add_u64 v[30:31], v[36:37], 0, s[12:13]
	v_lshlrev_b32_e32 v2, 2, v41
	s_mov_b64 s[12:13], 0xc400000
	v_add3_u32 v42, s17, v32, v2
	v_lshl_add_u64 v[32:33], v[36:37], 0, s[12:13]
	s_mov_b64 s[12:13], 0xbc00000
	v_lshl_add_u64 v[34:35], v[36:37], 0, s[12:13]
	s_mov_b64 s[12:13], 0xa600000
	s_sub_i32 s8, s20, s8
	v_or_b32_e32 v43, 8, v41
	v_or_b32_e32 v44, 16, v41
	v_or_b32_e32 v45, 24, v41
	v_lshl_add_u64 v[36:37], v[36:37], 0, s[12:13]
	s_lshl_b32 s17, s8, 3
	s_lshl_b32 s18, s16, 5
	s_lshl_b32 s19, s8, 8
	s_branch .LBB0_1592
.LBB0_1591:
	s_add_i32 s16, s16, s17
	s_add_i32 s18, s18, s19
	s_cmpk_lt_i32 s16, 0x34bc
	s_cbranch_scc0 .LBB0_1608

.LBB0_1710:
	s_abs_i32 s8, s22
	v_cvt_f32_u32_e32 v0, s8
	s_sub_i32 s9, 0, s8
	v_rcp_iflag_f32_e32 v0, v0
	s_nop 0
	v_mul_f32_e32 v0, 0x4f7ffffe, v0
	v_cvt_u32_f32_e32 v0, v0
	s_nop 0
	v_readfirstlane_b32 s12, v0
	s_mul_i32 s9, s9, s12
	s_mul_hi_u32 s9, s12, s9
	s_add_i32 s12, s12, s9
	s_mul_hi_u32 s9, s12, 0x23f
	s_mul_i32 s9, s9, s8
	s_sub_i32 s9, 0x23f, s9
	s_sub_i32 s12, s9, s8
	s_cmp_ge_u32 s9, s8
	s_cselect_b32 s9, s12, s9
	s_sub_i32 s12, s9, s8
	s_cmp_ge_u32 s9, s8
	s_cselect_b32 s8, s12, s9
	s_add_i32 s8, s8, 1
	s_cmp_lt_i32 s8, s22
	s_cselect_b32 s8, s8, 0
	s_cmp_lt_i32 s23, s8
	s_cbranch_scc1 .LBB0_1730
	s_sub_i32 s9, s23, s8
	s_lshl_b32 s9, s9, 3
	s_add_i32 s9, s24, s9
	s_add_i32 s16, s9, 0x34bc
	s_cmpk_gt_i32 s16, 0x5fbf
	s_waitcnt vmcnt(0)
	s_barrier
	s_cbranch_scc1 .LBB0_1730
	s_ashr_i32 s43, s42, 31
	s_lshl_b64 s[12:13], s[42:43], 3
	v_readlane_b32 s18, v253, 5
	v_readlane_b32 s19, v253, 6
	s_add_u32 s12, s18, s12
	s_addc_u32 s13, s19, s13
	s_load_dwordx2 s[18:19], s[12:13], 0x38
	s_mul_i32 s17, s38, 0x2b80000
	s_mul_hi_u32 s9, s38, 0x2b80000
	s_mov_b32 s39, s89
	v_bfe_u32 v1, v184, 5, 1
	s_waitcnt lgkmcnt(0)
	s_add_u32 s30, s18, s17
	s_addc_u32 s31, s19, s9
	s_load_dwordx2 s[18:19], s[12:13], 0xa0
	s_lshl_b64 s[20:21], s[38:39], 24
	s_mul_hi_u32 s9, s38, 0x2c00000
	v_and_b32_e32 v0, 31, v184
	v_lshlrev_b32_e32 v2, 2, v0
	s_waitcnt lgkmcnt(0)
	s_add_u32 s42, s18, s20
	s_addc_u32 s43, s19, s21
	s_load_dwordx2 s[18:19], s[12:13], 0xc0
	s_load_dwordx4 s[44:47], s[12:13], 0xb0
	s_mul_i32 s12, s38, 0x2c00000
	v_mul_u32_u24_e32 v28, 0x84, v1
	v_bfe_u32 v39, v184, 3, 3
	v_or_b32_e32 v41, 8, v39
	s_waitcnt lgkmcnt(0)
	s_add_u32 s44, s44, s12
	s_addc_u32 s45, s45, s9
	s_add_u32 s46, s46, s12
	s_addc_u32 s47, s47, s9
	s_add_u32 s48, s18, s12
	s_addc_u32 s49, s19, s9
	s_bitcmp1_b32 s38, 0
	s_cselect_b32 s9, 0x6000000, 0
	s_lshl_b32 s12, s24, 14
	s_add_i32 s17, s12, 0
	v_add3_u32 v38, s17, v2, v28
	v_lshlrev_b32_e32 v2, 3, v184
	s_add_u32 s12, s40, s9
	v_and_b32_e32 v2, 56, v2
	s_addc_u32 s13, s41, 0
	v_mul_u32_u24_e32 v30, 0x84, v2
	v_lshlrev_b32_e32 v2, 1, v2
	v_lshl_add_u64 v[34:35], s[12:13], 0, v[2:3]
	s_mov_b64 s[12:13], 0xf000000
	v_lshl_add_u64 v[28:29], v[34:35], 0, s[12:13]
	v_lshlrev_b32_e32 v2, 2, v39
	s_mov_b64 s[12:13], 0xc400000
	v_add3_u32 v40, s17, v30, v2
	v_lshl_add_u64 v[30:31], v[34:35], 0, s[12:13]
	s_mov_b64 s[12:13], 0xbc00000
	v_lshl_add_u64 v[32:33], v[34:35], 0, s[12:13]
	s_mov_b64 s[12:13], 0xa600000
	s_sub_i32 s8, s22, s8
	v_or_b32_e32 v42, 16, v39
	v_or_b32_e32 v43, 24, v39
	v_lshl_add_u64 v[34:35], v[34:35], 0, s[12:13]
	s_lshl_b32 s17, s8, 3
	s_lshl_b32 s18, s16, 5
	s_lshl_b32 s19, s8, 8
	s_branch .LBB0_1714
